# phase 0 x->bf16 loop: two rows per trip, 8 quarter-row loads in flight
# speedup vs baseline: 1.0045x; 1.0045x over previous
.LBB0_255:
	s_waitcnt lgkmcnt(0)
	global_load_dwordx4 v[16:19], v[8:9], off
	global_load_dwordx4 v[24:27], v[8:9], off offset:1024
	global_load_dwordx4 v[28:31], v[8:9], off offset:2048
	global_load_dwordx4 v[32:35], v[8:9], off offset:3072
	v_readfirstlane_b32 s32, v1
	s_nop 3
	s_add_i32 s32, s32, s8
	s_cmp_gt_i32 s32, s63
	s_cbranch_scc1 .Lx2_noB1
	v_lshl_add_u64 v[44:45], v[8:9], 0, s[14:15]
	v_lshl_add_u64 v[46:47], v[6:7], 0, s[12:13]
	v_lshl_add_u64 v[76:77], v[4:5], 0, s[10:11]
	global_load_dwordx4 v[48:51], v[44:45], off
	global_load_dwordx4 v[56:59], v[44:45], off offset:1024
	global_load_dwordx4 v[60:63], v[44:45], off offset:2048
	global_load_dwordx4 v[64:67], v[44:45], off offset:3072
	s_waitcnt vmcnt(7)
	v_mul_f32_e32 v2, v17, v17
	v_fmac_f32_e32 v2, v16, v16
	v_mul_f32_e32 v20, v19, v19
	v_fmac_f32_e32 v20, v18, v18
	v_cvt_pk_bf16_f32 v36, v16, v17
	v_cvt_pk_bf16_f32 v37, v18, v19
	v_add_f32_e32 v2, v2, v20
	global_store_dwordx2 v[6:7], v[36:37], off offset:-1024
	s_waitcnt vmcnt(7)
	v_mul_f32_e32 v20, v25, v25
	v_fmac_f32_e32 v20, v24, v24
	v_mul_f32_e32 v21, v27, v27
	v_fmac_f32_e32 v21, v26, v26
	v_cvt_pk_bf16_f32 v38, v24, v25
	v_cvt_pk_bf16_f32 v39, v26, v27
	v_add_f32_e32 v20, v20, v21
	v_add_f32_e32 v2, v2, v20
	global_store_dwordx2 v[6:7], v[38:39], off offset:-512
	s_waitcnt vmcnt(7)
	v_mul_f32_e32 v20, v29, v29
	v_fmac_f32_e32 v20, v28, v28
	v_mul_f32_e32 v21, v31, v31
	v_fmac_f32_e32 v21, v30, v30
	v_cvt_pk_bf16_f32 v40, v28, v29
	v_cvt_pk_bf16_f32 v41, v30, v31
	v_add_f32_e32 v20, v20, v21
	v_add_f32_e32 v2, v2, v20
	global_store_dwordx2 v[6:7], v[40:41], off
	s_waitcnt vmcnt(7)
	v_mul_f32_e32 v20, v33, v33
	v_fmac_f32_e32 v20, v32, v32
	v_mul_f32_e32 v21, v35, v35
	v_fmac_f32_e32 v21, v34, v34
	v_cvt_pk_bf16_f32 v42, v32, v33
	v_cvt_pk_bf16_f32 v43, v34, v35
	v_add_f32_e32 v20, v20, v21
	v_add_f32_e32 v2, v2, v20
	global_store_dwordx2 v[6:7], v[42:43], off offset:512
	v_mov_b32_e32 v16, v2
	s_nop 1
	v_permlane32_swap_b32_e32 v2, v16
	v_add_f32_e32 v2, v2, v16
	v_mov_b32_e32 v16, v2
	s_nop 1
	v_permlane16_swap_b32_e32 v2, v16
	v_add_f32_e32 v2, v2, v16
	s_nop 1
	v_add_f32_dpp v2, v2, v2 row_ror:8 row_mask:0xf bank_mask:0xf
	s_nop 1
	v_add_f32_dpp v2, v2, v2 row_ror:4 row_mask:0xf bank_mask:0xf
	s_nop 1
	v_add_f32_dpp v2, v2, v2 quad_perm:[2,3,0,1] row_mask:0xf bank_mask:0xf
	s_nop 1
	v_add_f32_dpp v2, v2, v2 quad_perm:[1,0,3,2] row_mask:0xf bank_mask:0xf
	s_mov_b64 s[82:83], exec
	s_and_saveexec_b64 s[4:5], vcc
	s_cbranch_execz .Lx2_a1
	v_cndmask_b32_e64 v2, 0, v2, s[0:1]
	global_store_dword v[4:5], v2, off
.Lx2_a1:
	s_mov_b64 exec, s[82:83]
	s_waitcnt vmcnt(4)
	v_mul_f32_e32 v78, v49, v49
	v_fmac_f32_e32 v78, v48, v48
	v_mul_f32_e32 v52, v51, v51
	v_fmac_f32_e32 v52, v50, v50
	v_cvt_pk_bf16_f32 v68, v48, v49
	v_cvt_pk_bf16_f32 v69, v50, v51
	v_add_f32_e32 v78, v78, v52
	global_store_dwordx2 v[46:47], v[68:69], off offset:-1024
	v_mul_f32_e32 v52, v57, v57
	v_fmac_f32_e32 v52, v56, v56
	v_mul_f32_e32 v53, v59, v59
	v_fmac_f32_e32 v53, v58, v58
	v_cvt_pk_bf16_f32 v70, v56, v57
	v_cvt_pk_bf16_f32 v71, v58, v59
	v_add_f32_e32 v52, v52, v53
	v_add_f32_e32 v78, v78, v52
	global_store_dwordx2 v[46:47], v[70:71], off offset:-512
	v_mul_f32_e32 v52, v61, v61
	v_fmac_f32_e32 v52, v60, v60
	v_mul_f32_e32 v53, v63, v63
	v_fmac_f32_e32 v53, v62, v62
	v_cvt_pk_bf16_f32 v72, v60, v61
	v_cvt_pk_bf16_f32 v73, v62, v63
	v_add_f32_e32 v52, v52, v53
	v_add_f32_e32 v78, v78, v52
	global_store_dwordx2 v[46:47], v[72:73], off
	v_mul_f32_e32 v52, v65, v65
	v_fmac_f32_e32 v52, v64, v64
	v_mul_f32_e32 v53, v67, v67
	v_fmac_f32_e32 v53, v66, v66
	v_cvt_pk_bf16_f32 v74, v64, v65
	v_cvt_pk_bf16_f32 v75, v66, v67
	v_add_f32_e32 v52, v52, v53
	v_add_f32_e32 v78, v78, v52
	global_store_dwordx2 v[46:47], v[74:75], off offset:512
	v_mov_b32_e32 v48, v78
	s_nop 1
	v_permlane32_swap_b32_e32 v78, v48
	v_add_f32_e32 v78, v78, v48
	v_mov_b32_e32 v48, v78
	s_nop 1
	v_permlane16_swap_b32_e32 v78, v48
	v_add_f32_e32 v78, v78, v48
	s_nop 1
	v_add_f32_dpp v78, v78, v78 row_ror:8 row_mask:0xf bank_mask:0xf
	s_nop 1
	v_add_f32_dpp v78, v78, v78 row_ror:4 row_mask:0xf bank_mask:0xf
	s_nop 1
	v_add_f32_dpp v78, v78, v78 quad_perm:[2,3,0,1] row_mask:0xf bank_mask:0xf
	s_nop 1
	v_add_f32_dpp v78, v78, v78 quad_perm:[1,0,3,2] row_mask:0xf bank_mask:0xf
	s_and_saveexec_b64 s[4:5], vcc
	s_cbranch_execz .Lx2_b1
	v_cndmask_b32_e64 v78, 0, v78, s[0:1]
	global_store_dword v[76:77], v78, off
.Lx2_b1:
	s_or_b64 exec, exec, s[4:5]
	v_add_u32_e32 v1, s8, v1
	v_lshl_add_u64 v[4:5], v[4:5], 0, s[10:11]
	v_lshl_add_u64 v[6:7], v[6:7], 0, s[12:13]
	v_lshl_add_u64 v[8:9], v[8:9], 0, s[14:15]
	s_mov_b64 s[4:5], 0
	s_branch .LBB0_254
.Lx2_noB1:
	s_waitcnt vmcnt(3)
	v_mul_f32_e32 v2, v17, v17
	v_fmac_f32_e32 v2, v16, v16
	v_mul_f32_e32 v20, v19, v19
	v_fmac_f32_e32 v20, v18, v18
	v_cvt_pk_bf16_f32 v36, v16, v17
	v_cvt_pk_bf16_f32 v37, v18, v19
	v_add_f32_e32 v2, v2, v20
	global_store_dwordx2 v[6:7], v[36:37], off offset:-1024
	s_waitcnt vmcnt(3)
	v_mul_f32_e32 v20, v25, v25
	v_fmac_f32_e32 v20, v24, v24
	v_mul_f32_e32 v21, v27, v27
	v_fmac_f32_e32 v21, v26, v26
	v_cvt_pk_bf16_f32 v38, v24, v25
	v_cvt_pk_bf16_f32 v39, v26, v27
	v_add_f32_e32 v20, v20, v21
	v_add_f32_e32 v2, v2, v20
	global_store_dwordx2 v[6:7], v[38:39], off offset:-512
	s_waitcnt vmcnt(3)
	v_mul_f32_e32 v20, v29, v29
	v_fmac_f32_e32 v20, v28, v28
	v_mul_f32_e32 v21, v31, v31
	v_fmac_f32_e32 v21, v30, v30
	v_cvt_pk_bf16_f32 v40, v28, v29
	v_cvt_pk_bf16_f32 v41, v30, v31
	v_add_f32_e32 v20, v20, v21
	v_add_f32_e32 v2, v2, v20
	global_store_dwordx2 v[6:7], v[40:41], off
	s_waitcnt vmcnt(3)
	v_mul_f32_e32 v20, v33, v33
	v_fmac_f32_e32 v20, v32, v32
	v_mul_f32_e32 v21, v35, v35
	v_fmac_f32_e32 v21, v34, v34
	v_cvt_pk_bf16_f32 v42, v32, v33
	v_cvt_pk_bf16_f32 v43, v34, v35
	v_add_f32_e32 v20, v20, v21
	v_add_f32_e32 v2, v2, v20
	global_store_dwordx2 v[6:7], v[42:43], off offset:512
	v_mov_b32_e32 v16, v2
	s_nop 1
	v_permlane32_swap_b32_e32 v2, v16
	v_add_f32_e32 v2, v2, v16
	v_mov_b32_e32 v16, v2
	s_nop 1
	v_permlane16_swap_b32_e32 v2, v16
	v_add_f32_e32 v2, v2, v16
	s_nop 1
	v_add_f32_dpp v2, v2, v2 row_ror:8 row_mask:0xf bank_mask:0xf
	s_nop 1
	v_add_f32_dpp v2, v2, v2 row_ror:4 row_mask:0xf bank_mask:0xf
	s_nop 1
	v_add_f32_dpp v2, v2, v2 quad_perm:[2,3,0,1] row_mask:0xf bank_mask:0xf
	s_nop 1
	v_add_f32_dpp v2, v2, v2 quad_perm:[1,0,3,2] row_mask:0xf bank_mask:0xf
	s_and_saveexec_b64 s[4:5], vcc
	s_cbranch_execz .LBB0_254
	v_cndmask_b32_e64 v2, 0, v2, s[0:1]
	global_store_dword v[4:5], v2, off
	s_branch .LBB0_254
